# v36 plus P9: the dead-row staging loads of waves 6-7 read one hot 1 KB block instead of streaming unused rows
# speedup vs baseline: 1.0007x; 1.0007x over previous
.LBB0_640:
	s_or_b64 exec, exec, s[6:7]
	v_readlane_b32 s0, v242, 38
	v_readlane_b32 s1, v242, 39
	s_waitcnt lgkmcnt(0)
	s_barrier
	s_and_b64 vcc, exec, s[0:1]
	v_readfirstlane_b32 s34, v0
	v_lshlrev_b32_e32 v1, 4, v0
	v_add_u32_e32 v2, 0x2000, v1
	v_ashrrev_i32_e32 v3, 31, v2
	v_lshrrev_b32_e32 v3, 22, v3
	v_add_u32_e32 v3, v2, v3
	v_ashrrev_i32_e32 v10, 10, v3
	v_mul_i32_i24_e32 v3, 0x400, v10
	v_sub_u32_e32 v2, v2, v3
	v_lshrrev_b32_e32 v3, 4, v2
	v_bitop3_b32 v2, v3, v2, 32 bitop3:0x6c
	v_ashrrev_i32_e32 v3, 31, v2
	v_lshrrev_b32_e32 v3, 26, v3
	v_add_u32_e32 v3, v2, v3
	v_lshlrev_b32_e32 v4, 3, v10
	v_ashrrev_i32_e32 v11, 6, v3
	v_and_b32_e32 v4, -16, v4
	v_add_u32_e32 v4, v11, v4
	v_and_b32_e32 v5, 3, v11
	s_mov_b32 s0, 0x7ffe0
	v_lshrrev_b32_e32 v6, 2, v4
	v_lshlrev_b32_e32 v7, 1, v4
	v_and_b32_e32 v3, 0xc0, v3
	v_and_or_b32 v5, v4, s0, v5
	v_and_b32_e32 v6, 4, v6
	v_and_b32_e32 v7, 24, v7
	v_sub_u32_e32 v2, v2, v3
	v_mov_b32_e32 v3, 1
	v_or3_b32 v5, v5, v6, v7
	v_lshlrev_b32_e32 v6, 5, v10
	v_ashrrev_i16_sdwa v2, v3, sext(v2) dst_sel:DWORD dst_unused:UNUSED_PAD src0_sel:DWORD src1_sel:BYTE_0
	v_and_b32_e32 v6, 32, v6
	v_bfe_i32 v12, v2, 0, 16
	v_add_lshl_u32 v2, v6, v12, 1
	v_lshl_add_u32 v122, v5, 13, v2
	v_lshl_add_u32 v124, v4, 13, v2
	v_add_u32_e32 v124, 0xfffe0000, v124
	v_bfe_i32 v2, v0, 27, 1
	v_lshrrev_b32_e32 v2, 22, v2
	v_add_u32_e32 v2, v1, v2
	v_and_b32_e32 v2, 0xfffffc00, v2
	v_sub_u32_e32 v1, v1, v2
	v_lshrrev_b32_e32 v2, 4, v1
	v_ashrrev_i32_e32 v4, 31, v0
	v_bitop3_b32 v1, v2, v1, 32 bitop3:0x6c
	v_lshrrev_b32_e32 v4, 26, v4
	v_ashrrev_i32_e32 v2, 31, v1
	v_add_u32_e32 v4, v0, v4
	v_lshrrev_b32_e32 v2, 26, v2
	v_ashrrev_i32_e32 v14, 6, v4
	v_add_u32_e32 v2, v1, v2
	v_lshlrev_b32_e32 v4, 3, v14
	v_ashrrev_i32_e32 v13, 6, v2
	v_and_b32_e32 v4, -16, v4
	v_add_u32_e32 v4, v13, v4
	v_and_b32_e32 v5, 3, v13
	s_ashr_i32 s36, s38, 31
	v_and_or_b32 v5, v4, s0, v5
	s_lshr_b32 s0, s36, 29
	s_add_i32 s0, s38, s0
	s_ashr_i32 s3, s34, 6
	s_ashr_i32 s1, s0, 3
	s_and_b32 s0, s0, -8
	s_ashr_i32 s11, s34, 8
	s_lshl_b32 s35, s3, 10
	s_sub_i32 s0, s38, s0
	s_cmp_lt_i32 s0, 0
	s_cselect_b32 s4, 25, 24
	s_mul_i32 s0, s0, s4
	s_add_i32 s0, s0, s1
	s_mul_hi_i32 s1, s0, 0x2aaaaaab
	s_lshr_b32 s4, s1, 31
	s_ashr_i32 s1, s1, 2
	s_add_i32 s1, s1, s4
	s_mul_i32 s4, s1, 6
	s_mul_i32 s1, s1, 24
	s_sub_i32 s1, s0, s1
	s_mul_i32 s0, s1, 43
	s_bfe_u32 s5, s0, 0x1000f
	s_bfe_u32 s0, s0, 0x80008
	s_add_i32 s0, s0, s5
	s_mul_i32 s5, s0, 6
	s_sub_i32 s1, s1, s5
	s_sext_i32_i8 s1, s1
	v_lshrrev_b32_e32 v6, 2, v4
	v_lshlrev_b32_e32 v7, 1, v4
	v_and_b32_e32 v2, 0xc0, v2
	s_add_i32 s6, s4, s1
	v_and_b32_e32 v6, 4, v6
	v_and_b32_e32 v7, 24, v7
	v_sub_u32_e32 v1, v1, v2
	s_lshr_b32 s1, s38, 3
	s_and_b32 s0, s1, 3
	s_lshr_b32 s1, s1, 2
	s_and_b32 s6, s38, 7
	s_lshl_b32 s6, s6, 3
	s_add_i32 s6, s6, s1
	s_ashr_i32 s7, s6, 31
	s_bfe_i64 s[14:15], s[0:1], 0x80000
	v_or3_b32 v5, v5, v6, v7
	v_lshlrev_b32_e32 v6, 5, v14
	v_ashrrev_i16_sdwa v1, v3, sext(v1) dst_sel:DWORD dst_unused:UNUSED_PAD src0_sel:DWORD src1_sel:BYTE_0
	s_mul_i32 s4, s6, 0x180000
	s_mov_b32 s5, 0
	s_lshl_b64 s[14:15], s[14:15], 21
	v_and_b32_e32 v6, 32, v6
	v_bfe_i32 v15, v1, 0, 16
	s_add_u32 s26, s86, s14
	v_add_lshl_u32 v1, v6, v15, 1
	s_addc_u32 s27, s87, s15
	s_add_i32 s37, s35, 0
	v_lshl_add_u32 v134, v5, 13, v1
	s_add_i32 m0, s37, 0x10000
	v_lshl_add_u32 v136, v4, 13, v1
	v_and_b32_e32 v240, 63, v0
	v_lshlrev_b32_e32 v240, 4, v240
	s_cmp_gt_u32 s34, 0x17f
	s_cselect_b64 vcc, -1, 0
	s_nop 0
	v_cndmask_b32_e32 v124, v124, v240, vcc
	v_cndmask_b32_e32 v136, v136, v240, vcc
	global_load_lds_dwordx4 v134, s[26:27]
	s_add_i32 m0, s37, 0x12000
	s_add_u32 s14, s26, 0x100000
	global_load_lds_dwordx4 v122, s[26:27]
	s_addc_u32 s15, s27, 0
	s_add_i32 m0, s37, 0x14000
	v_mov_b32_e32 v135, 0
	global_load_lds_dwordx4 v134, s[14:15]
	s_add_i32 m0, s37, 0x16000
	v_mov_b32_e32 v123, v135
	global_load_lds_dwordx4 v122, s[14:15]
	s_add_u32 s14, s68, s4
	s_addc_u32 s15, s69, s5
	s_add_i32 s41, s37, 0x2000
	s_mov_b32 m0, s37
	s_add_u32 s4, s14, 0xc0000
	global_load_lds_dwordx4 v136, s[14:15]
	s_mov_b32 m0, s41
	s_addc_u32 s5, s15, 0
	s_add_i32 s42, s37, 0x4000
	global_load_lds_dwordx4 v124, s[14:15]
	s_mov_b32 m0, s42
	s_add_i32 s43, s37, 0x6000
	global_load_lds_dwordx4 v136, s[4:5]
	s_mov_b32 m0, s43
	v_mov_b32_e32 v137, v135
	global_load_lds_dwordx4 v124, s[4:5]
	v_mov_b32_e32 v125, v135
	s_mov_b32 s44, 0
	v_lshl_add_u64 v[8:9], s[26:27], 0, v[134:135]
	v_lshl_add_u64 v[6:7], s[26:27], 0, v[122:123]
	v_lshl_add_u64 v[4:5], s[14:15], 0, v[136:137]
	s_cmp_lg_u32 s11, 1
	v_lshl_add_u64 v[2:3], s[14:15], 0, v[124:125]
	s_cbranch_scc1 .LBB0_643
	s_barrier
.LBB0_643:
	v_and_b32_e32 v1, 15, v0
	v_and_b32_e32 v16, 48, v0
	v_lshlrev_b32_e32 v17, 2, v0
	s_mov_b64 s[16:17], 0x80
	s_sext_i32_i8 s10, s0
	s_and_b32 s7, s3, 3
	s_lshl_b32 s0, s11, 13
	v_lshl_or_b32 v16, v1, 6, v16
	v_and_b32_e32 v17, 32, v17
	s_add_i32 m0, s37, 0x18000
	v_lshl_add_u64 v[8:9], v[8:9], 0, s[16:17]
	s_lshl_b32 s40, s11, 6
	v_bitop3_b32 v18, v16, s0, v17 bitop3:0xde
	s_lshl_b32 s0, s7, 12
	s_waitcnt vmcnt(2)
	s_barrier
	global_load_lds_dwordx4 v[8:9], off
	v_lshl_add_u64 v[6:7], v[6:7], 0, s[16:17]
	s_add_i32 m0, s37, 0x1a000
	s_add_i32 s45, s37, 0x8000
	s_add_i32 s56, s37, 0xa000
	global_load_lds_dwordx4 v[6:7], off
	v_lshl_add_u64 v[4:5], v[4:5], 0, s[16:17]
	s_mov_b32 m0, s45
	s_add_u32 s4, s26, 0x100080
	global_load_lds_dwordx4 v[4:5], off
	v_lshl_add_u64 v[2:3], v[2:3], 0, s[16:17]
	s_mov_b32 m0, s56
	s_addc_u32 s5, s27, 0
	global_load_lds_dwordx4 v[2:3], off
	s_add_i32 m0, s37, 0x1c000
	v_lshl_add_u64 v[2:3], s[4:5], 0, v[134:135]
	global_load_lds_dwordx4 v[2:3], off
	v_lshl_add_u64 v[2:3], s[4:5], 0, v[122:123]
	s_add_i32 m0, s37, 0x1e000
	v_bitop3_b32 v150, v16, s0, v17 bitop3:0xde
	global_load_lds_dwordx4 v[2:3], off
	v_lshlrev_b32_e32 v2, 16, v14
	v_and_b32_e32 v2, 0xfffe0000, v2
	v_lshl_add_u32 v2, v13, 13, v2
	v_and_b32_e32 v3, 1, v14
	v_lshl_or_b32 v2, v3, 6, v2
	s_mov_b64 s[0:1], 0xc0080
	v_lshl_add_u32 v2, v15, 1, v2
	v_mov_b32_e32 v3, v135
	v_lshl_add_u64 v[138:139], v[2:3], 0, s[0:1]
	s_cmp_gt_u32 s34, 0x17f
	s_cselect_b64 vcc, -1, 0
	v_add_u32_e32 v241, 0xc0080, v240
	v_cndmask_b32_e32 v138, v138, v241, vcc
	v_lshlrev_b32_e32 v2, 16, v10
	v_and_b32_e32 v2, 0xfffe0000, v2
	v_lshl_add_u32 v2, v11, 13, v2
	v_and_b32_e32 v3, 1, v10
	s_waitcnt vmcnt(6)
	v_lshl_or_b32 v2, v3, 6, v2
	v_lshl_add_u32 v2, v12, 1, v2
	v_mov_b32_e32 v3, v135
	v_or_b32_e32 v172, s40, v1
	v_add_u32_e32 v2, 0xfffe0000, v2
	v_lshl_add_u64 v[140:141], v[2:3], 0, s[0:1]
	s_cmp_gt_u32 s34, 0x17f
	s_cselect_b64 vcc, -1, 0
	v_add_u32_e32 v241, 0xc0080, v240
	v_cndmask_b32_e32 v140, v140, v241, vcc
	v_mov_b64_e32 v[142:143], 0xc0
	v_mov_b64_e32 v[144:145], 0xbf
	s_add_i32 s57, 0, 0x10000
	s_add_i32 s58, 0, 0x14000
	v_add_u32_e32 v151, 0, v18
	v_mov_b32_e32 v2, v135
	v_mov_b32_e32 v4, v135
	v_mov_b32_e32 v5, v135
	v_mov_b32_e32 v6, v135
	v_mov_b32_e32 v7, v135
	v_mov_b32_e32 v8, v135
	v_mov_b32_e32 v9, v135
	v_mov_b32_e32 v14, v135
	v_mov_b32_e32 v15, v135
	v_mov_b32_e32 v16, v135
	v_mov_b32_e32 v17, v135
	v_mov_b32_e32 v22, v135
	v_mov_b32_e32 v23, v135
	v_mov_b32_e32 v24, v135
	v_mov_b32_e32 v25, v135
	v_mov_b32_e32 v30, v135
	v_mov_b32_e32 v31, v135
	v_mov_b32_e32 v32, v135
	v_mov_b32_e32 v33, v135
	v_mov_b32_e32 v38, v135
	v_mov_b32_e32 v39, v135
	v_mov_b32_e32 v40, v135
	v_mov_b32_e32 v41, v135
	v_mov_b32_e32 v46, v135
	v_mov_b32_e32 v47, v135
	v_mov_b32_e32 v48, v135
	v_mov_b32_e32 v49, v135
	v_mov_b32_e32 v54, v135
	v_mov_b32_e32 v55, v135
	v_mov_b32_e32 v56, v135
	v_mov_b32_e32 v57, v135
	v_mov_b32_e32 v10, v135
	v_mov_b32_e32 v11, v135
	v_mov_b32_e32 v12, v135
	v_mov_b32_e32 v13, v135
	v_mov_b32_e32 v18, v135
	v_mov_b32_e32 v19, v135
	v_mov_b32_e32 v20, v135
	v_mov_b32_e32 v21, v135
	v_mov_b32_e32 v26, v135
	v_mov_b32_e32 v27, v135
	v_mov_b32_e32 v28, v135
	v_mov_b32_e32 v29, v135
	v_mov_b32_e32 v34, v135
	v_mov_b32_e32 v35, v135
	v_mov_b32_e32 v36, v135
	v_mov_b32_e32 v37, v135
	v_mov_b32_e32 v42, v135
	v_mov_b32_e32 v43, v135
	v_mov_b32_e32 v44, v135
	v_mov_b32_e32 v45, v135
	v_mov_b32_e32 v50, v135
	v_mov_b32_e32 v51, v135
	v_mov_b32_e32 v52, v135
	v_mov_b32_e32 v53, v135
	v_mov_b32_e32 v58, v135
	v_mov_b32_e32 v59, v135
	v_mov_b32_e32 v60, v135
	v_mov_b32_e32 v61, v135
	v_mov_b32_e32 v62, v135
	v_mov_b32_e32 v63, v135
	v_mov_b32_e32 v64, v135
	v_mov_b32_e32 v65, v135
	v_mov_b32_e32 v66, v135
	v_mov_b32_e32 v67, v135
	v_mov_b32_e32 v68, v135
	v_mov_b32_e32 v69, v135
	v_mov_b32_e32 v70, v135
	v_mov_b32_e32 v71, v135
	v_mov_b32_e32 v72, v135
	v_mov_b32_e32 v73, v135
	v_mov_b32_e32 v94, v135
	v_mov_b32_e32 v95, v135
	v_mov_b32_e32 v96, v135
	v_mov_b32_e32 v97, v135
	v_mov_b32_e32 v110, v135
	v_mov_b32_e32 v111, v135
	v_mov_b32_e32 v112, v135
	v_mov_b32_e32 v113, v135
	v_mov_b32_e32 v90, v135
	v_mov_b32_e32 v91, v135
	v_mov_b32_e32 v92, v135
	v_mov_b32_e32 v93, v135
	v_mov_b32_e32 v86, v135
	v_mov_b32_e32 v87, v135
	v_mov_b32_e32 v88, v135
	v_mov_b32_e32 v89, v135
	v_mov_b32_e32 v82, v135
	v_mov_b32_e32 v83, v135
	v_mov_b32_e32 v84, v135
	v_mov_b32_e32 v85, v135
	v_mov_b32_e32 v98, v135
	v_mov_b32_e32 v99, v135
	v_mov_b32_e32 v100, v135
	v_mov_b32_e32 v101, v135
	v_mov_b32_e32 v74, v135
	v_mov_b32_e32 v75, v135
	v_mov_b32_e32 v76, v135
	v_mov_b32_e32 v77, v135
	v_mov_b32_e32 v102, v135
	v_mov_b32_e32 v103, v135
	v_mov_b32_e32 v104, v135
	v_mov_b32_e32 v105, v135
	v_mov_b32_e32 v118, v135
	v_mov_b32_e32 v119, v135
	v_mov_b32_e32 v120, v135
	v_mov_b32_e32 v121, v135
	v_mov_b32_e32 v126, v135
	v_mov_b32_e32 v127, v135
	v_mov_b32_e32 v128, v135
	v_mov_b32_e32 v129, v135
	v_mov_b32_e32 v78, v135
	v_mov_b32_e32 v79, v135
	v_mov_b32_e32 v80, v135
	v_mov_b32_e32 v81, v135
	v_mov_b32_e32 v130, v135
	v_mov_b32_e32 v131, v135
	v_mov_b32_e32 v132, v135
	v_mov_b32_e32 v133, v135
	v_mov_b32_e32 v106, v135
	v_mov_b32_e32 v107, v135
	v_mov_b32_e32 v108, v135
	v_mov_b32_e32 v109, v135
	v_mov_b32_e32 v114, v135
	v_mov_b32_e32 v115, v135
	v_mov_b32_e32 v116, v135
	v_mov_b32_e32 v117, v135
	s_barrier
	s_branch .LBB0_646
